# norm phase row loop: L2 touch of the row after next (one dword per 64 B, latent rows) in front of the next row's loads
# baseline (speedup 1.0000x reference)
.LBB0_652:
	s_add_i32 s55, s96, s34
	s_cmp_ge_i32 s55, s1
	s_cselect_b64 s[50:51], -1, 0
	s_and_b64 vcc, exec, s[50:51]
	s_waitcnt vmcnt(3)
	v_mov_b32_e32 v64, v28
	v_mov_b32_e32 v65, v29
	v_mov_b32_e32 v66, v30
	v_mov_b32_e32 v67, v31
	s_waitcnt vmcnt(2)
	v_mov_b32_e32 v68, v24
	v_mov_b32_e32 v69, v25
	v_mov_b32_e32 v70, v26
	v_mov_b32_e32 v71, v27
	s_waitcnt vmcnt(1)
	v_mov_b32_e32 v72, v20
	v_mov_b32_e32 v73, v21
	v_mov_b32_e32 v74, v22
	v_mov_b32_e32 v75, v23
	s_waitcnt vmcnt(0)
	v_mov_b32_e32 v76, v16
	v_mov_b32_e32 v77, v17
	v_mov_b32_e32 v78, v18
	v_mov_b32_e32 v79, v19
	s_cbranch_vccnz .LBB0_654
	s_add_i32 s98, s55, s34
	s_cmp_lt_i32 s98, 0x8000
	s_cbranch_scc0 .Lnorm_notouch
	s_mov_b32 s99, 0
	s_lshl_b64 s[98:99], s[98:99], 12
	s_add_u32 s98, s41, s98
	s_addc_u32 s99, s40, s99
	v_lshlrev_b32_e32 v127, 6, v85
	global_load_dword v126, v127, s[98:99]
.Lnorm_notouch:
	s_add_i32 s2, s55, 0xffff8000
	s_cmp_lt_i32 s55, 0x8000
	s_cselect_b32 s3, s52, 0
	s_cselect_b32 s2, s29, s2
	s_cselect_b32 s30, s40, s4
	s_cselect_b32 s31, s41, s5
	s_lshl_b64 s[2:3], s[2:3], 12
	s_add_u32 s2, s31, s2
	s_addc_u32 s3, s30, s3
	global_load_dwordx4 v[64:67], v80, s[2:3]
	global_load_dwordx4 v[68:71], v80, s[2:3] offset:1024
	global_load_dwordx4 v[72:75], v80, s[2:3] offset:2048
	global_load_dwordx4 v[76:79], v80, s[2:3] offset:3072
